# LayerNorm-2 row loops: next iteration's rows touched (L2 prefetch) once the current rows have arrived
# speedup vs baseline: 1.0029x; 1.0029x over previous
; DI float bperm(float v, int srclane) { return __int_as_float(__builtin_amdgcn_ds_bpermute(srclane << 2, __float_as_int(v))); }
; DI void ln_rows2_f32(float* xa, float* xb, const float* g, const float* b, int lane, bool two) {
;     f32x4* xr[2] = {(f32x4*)xa, (f32x4*)xb}; f32x4 v[2][4]; float s[2] = {0.f, 0.f}, s2[2] = {0.f, 0.f}, mean[2], rstd[2];
; #pragma unroll
;     for (int r = 0; r < 2; ++r)
; #pragma unroll
;         for (int j = 0; j < 4; ++j) v[r][j] = xr[r][lane + 64 * j];
; #pragma unroll
;     for (int r = 0; r < 2; ++r)
; #pragma unroll
;         for (int j = 0; j < 4; ++j) s[r] += (v[r][j][0] + v[r][j][1]) + (v[r][j][2] + v[r][j][3]);
; #pragma unroll
;     for (int o = 1; o < 64; o <<= 1) { s[0] += bperm(s[0], lane ^ o); s[1] += bperm(s[1], lane ^ o); }
; __global__ void __launch_bounds__(512, 2) hybrid_fwd(Args unused_args) {
;     ...
;           else { for (int m = gw; m < T; m += 2 * NGW) { const int m2 = m + NGW < T ? m + NGW : m; ln_rows2_f32(a.out + (size_t)m * DMODEL, a.out + (size_t)m2 * DMODEL, P.ln2g, P.ln2b, lane, m2 != m); } } }
.LBB0_2104:
	s_add_i32 s13, s2, s7
	s_cmp_lt_i32 s13, 0x8000
	s_cselect_b32 s20, s13, s2
	s_ashr_i32 s3, s2, 31
	s_lshl_b64 s[14:15], s[2:3], 12
	v_lshl_add_u64 v[46:47], v[44:45], 0, s[14:15]
	global_load_dwordx4 v[30:33], v[46:47], off
	global_load_dwordx4 v[26:29], v[46:47], off offset:1024
	global_load_dwordx4 v[14:17], v[46:47], off offset:2048
	global_load_dwordx4 v[10:13], v[46:47], off offset:3072
	s_ashr_i32 s21, s20, 31
	s_lshl_b64 s[14:15], s[20:21], 12
	v_lshl_add_u64 v[48:49], v[44:45], 0, s[14:15]
	global_load_dwordx4 v[22:25], v[48:49], off
	global_load_dwordx4 v[18:21], v[48:49], off offset:1024
	global_load_dwordx4 v[6:9], v[48:49], off offset:2048
	global_load_dwordx4 v[2:5], v[48:49], off offset:3072
	s_mov_b32 s3, 0xf800000
	s_cmp_lg_u32 s2, s20
	s_cselect_b64 s[34:35], -1, 0
	s_cmp_eq_u32 s2, s20
	s_waitcnt vmcnt(7)
	v_mov_b32_e32 v34, v31
	v_mov_b32_e32 v35, v32
	v_mov_b32_e32 v36, v30
	v_mov_b32_e32 v37, v33
	s_waitcnt vmcnt(6)
	v_mov_b32_e32 v50, v27
	v_mov_b32_e32 v51, v28
	v_mov_b32_e32 v52, v26
	v_mov_b32_e32 v53, v29
	s_waitcnt vmcnt(5)
	v_add_f32_e32 v54, v14, v15
	v_add_f32_e32 v56, v16, v17
	s_waitcnt vmcnt(4)
	v_mov_b32_e32 v55, v12
	v_mov_b32_e32 v57, v13
	v_pk_add_f32 v[34:35], v[34:35], v[36:37]
	v_pk_add_f32 v[36:37], v[50:51], v[52:53]
	v_pk_add_f32 v[50:51], v[54:55], v[56:57]
	s_waitcnt vmcnt(3)
	v_mov_b32_e32 v52, v23
	v_mov_b32_e32 v53, v24
	v_mov_b32_e32 v54, v22
	v_mov_b32_e32 v55, v25
	s_waitcnt vmcnt(2)
	v_mov_b32_e32 v56, v19
	v_mov_b32_e32 v57, v20
	v_mov_b32_e32 v66, v18
	v_mov_b32_e32 v67, v21
	v_add_f32_e32 v0, v34, v35
	v_pk_add_f32 v[34:35], v[36:37], v[36:37] op_sel:[0,1] op_sel_hi:[1,0]
	v_pk_add_f32 v[36:37], v[52:53], v[54:55]
	v_pk_add_f32 v[52:53], v[56:57], v[66:67]
	v_mov_b32_e32 v65, v10
	v_add_f32_e32 v64, 0, v0
	v_mov_b32_e32 v35, v11
	v_add_f32_e32 v0, v36, v37
	v_pk_add_f32 v[36:37], v[52:53], v[52:53] op_sel:[0,1] op_sel_hi:[1,0]
	s_waitcnt vmcnt(1)
	v_add_f32_e32 v68, v6, v7
	v_add_f32_e32 v70, v8, v9
	s_waitcnt vmcnt(0)
	v_mov_b32_e32 v140, s13
	v_add_u32_e32 v140, s7, v140
	v_mov_b32_e32 v142, 0x8000
	v_cmp_lt_i32_e64 s[14:15], v140, v142
	v_add_u32_e32 v142, s7, v140
	v_lshlrev_b32_e32 v140, 12, v140
	v_lshlrev_b32_e32 v142, 12, v142
	v_mov_b32_e32 v141, 0
	v_mov_b32_e32 v143, 0
	v_lshl_add_u64 v[140:141], v[44:45], 0, v[140:141]
	v_lshl_add_u64 v[142:143], v[44:45], 0, v[142:143]
	s_mov_b64 exec, s[14:15]
	global_load_dwordx4 v[144:147], v[140:141], off
	global_load_dwordx4 v[144:147], v[140:141], off offset:1024
	global_load_dwordx4 v[144:147], v[140:141], off offset:2048
	global_load_dwordx4 v[144:147], v[140:141], off offset:3072
	global_load_dwordx4 v[144:147], v[142:143], off
	global_load_dwordx4 v[144:147], v[142:143], off offset:1024
	global_load_dwordx4 v[144:147], v[142:143], off offset:2048
	global_load_dwordx4 v[144:147], v[142:143], off offset:3072
	s_mov_b64 exec, -1
	v_mov_b32_e32 v73, v2
	v_mov_b32_e32 v69, v4
	v_mov_b32_e32 v71, v5
	v_pk_add_f32 v[34:35], v[64:65], v[34:35]
	v_add_f32_e32 v72, 0, v0
	v_mov_b32_e32 v37, v3
	v_pk_add_f32 v[54:55], v[68:69], v[70:71]
	v_pk_add_f32 v[34:35], v[34:35], v[50:51]
	v_pk_add_f32 v[36:37], v[72:73], v[36:37]
	v_add_f32_e32 v0, v34, v35
	v_pk_add_f32 v[34:35], v[36:37], v[54:55]
	s_nop 0
	v_add_f32_e32 v34, v34, v35
	ds_bpermute_b32 v35, v58, v0
	ds_bpermute_b32 v36, v58, v34
	s_waitcnt lgkmcnt(1)
	v_add_f32_e32 v0, v0, v35
	ds_bpermute_b32 v35, v59, v0
	s_waitcnt lgkmcnt(1)
	v_add_f32_e32 v34, v34, v36
	ds_bpermute_b32 v36, v59, v34
	s_waitcnt lgkmcnt(1)
	v_add_f32_e32 v0, v0, v35
	ds_bpermute_b32 v35, v60, v0
	s_waitcnt lgkmcnt(1)
	v_add_f32_e32 v34, v34, v36
	ds_bpermute_b32 v36, v60, v34
	s_waitcnt lgkmcnt(1)
	v_add_f32_e32 v0, v0, v35
	ds_bpermute_b32 v35, v61, v0
	s_waitcnt lgkmcnt(1)
	v_add_f32_e32 v34, v34, v36
	ds_bpermute_b32 v36, v61, v34
	s_waitcnt lgkmcnt(1)
	v_add_f32_e32 v0, v0, v35
	ds_bpermute_b32 v35, v62, v0
	s_waitcnt lgkmcnt(1)
	v_add_f32_e32 v34, v34, v36
	ds_bpermute_b32 v36, v62, v34
	s_waitcnt lgkmcnt(1)
	v_add_f32_e32 v0, v0, v35
	ds_bpermute_b32 v35, v63, v0
	s_waitcnt lgkmcnt(1)
	v_add_f32_e32 v34, v34, v36
	ds_bpermute_b32 v36, v63, v34
	s_waitcnt lgkmcnt(1)
	v_add_f32_e32 v0, v0, v35
	v_fmamk_f32 v55, v0, 0xba800000, v31
	v_fmamk_f32 v54, v0, 0xba800000, v30
	v_fmamk_f32 v33, v0, 0xba800000, v33
	v_fmac_f32_e32 v32, 0xba800000, v0
	v_fmamk_f32 v53, v0, 0xba800000, v29
	v_fmamk_f32 v52, v0, 0xba800000, v28
	v_fmamk_f32 v27, v0, 0xba800000, v27
	v_fmac_f32_e32 v26, 0xba800000, v0
	s_waitcnt lgkmcnt(0)
; DI float bperm(float v, int srclane) { return __int_as_float(__builtin_amdgcn_ds_bpermute(srclane << 2, __float_as_int(v))); }
; DI void ln_rows2_f32(float* xa, float* xb, const float* g, const float* b, int lane, bool two) {
;     ...
;     for (int r = 0; r < 2; ++r) { mean[r] = s[r] * (1.f / 1024.f);
; #pragma unroll
;         for (int j = 0; j < 4; ++j) { v[r][j] = v[r][j] - mean[r]; s2[r] += (v[r][j][0] * v[r][j][0] + v[r][j][1] * v[r][j][1]) + (v[r][j][2] * v[r][j][2] + v[r][j][3] * v[r][j][3]); } }
; #pragma unroll
;     for (int o = 1; o < 64; o <<= 1) { s2[0] += bperm(s2[0], lane ^ o); s2[1] += bperm(s2[1], lane ^ o); }
; #pragma unroll
;     for (int r = 0; r < 2; ++r) rstd[r] = 1.f / sqrtf(s2[r] * (1.f / 1024.f) + EPS);
; #pragma unroll
;     for (int j = 0; j < 4; ++j) { const f32x4 gg = ((const f32x4*)g)[lane + 64 * j], bb = ((const f32x4*)b)[lane + 64 * j];
; #pragma unroll
;         for (int r = 0; r < 2; ++r) if (r == 0 || two) xr[r][lane + 64 * j] = v[r][j] * rstd[r] * gg + bb; }
	v_add_f32_e32 v66, v34, v36
	v_pk_mul_f32 v[28:29], v[32:33], v[32:33]
	v_pk_mul_f32 v[30:31], v[54:55], v[54:55]
	v_pk_mul_f32 v[34:35], v[52:53], v[52:53]
	v_pk_mul_f32 v[36:37], v[26:27], v[26:27]
	v_fmamk_f32 v50, v0, 0xba800000, v16
	v_fmac_f32_e32 v14, 0xba800000, v0
	v_pk_mov_b32 v[56:57], v[30:31], v[28:29] op_sel:[1,0]
	v_mov_b32_e32 v31, v29
	v_pk_mov_b32 v[28:29], v[36:37], v[34:35] op_sel:[1,0]
	v_mov_b32_e32 v37, v35
	v_fmamk_f32 v51, v0, 0xba800000, v17
	v_fmamk_f32 v15, v0, 0xba800000, v15
	v_fmamk_f32 v13, v0, 0xba800000, v13
	v_fmamk_f32 v12, v0, 0xba800000, v12
	v_fmamk_f32 v11, v0, 0xba800000, v11
	v_fmac_f32_e32 v10, 0xba800000, v0
	v_mul_f32_e32 v0, v14, v14
	v_mul_f32_e32 v16, v50, v50
	v_fmamk_f32 v17, v66, 0xba800000, v21
	v_pk_add_f32 v[30:31], v[56:57], v[30:31]
	v_pk_add_f32 v[28:29], v[28:29], v[36:37]
	v_pk_fma_f32 v[34:35], v[14:15], v[14:15], v[0:1] op_sel_hi:[1,1,0]
	v_pk_fma_f32 v[64:65], v[50:51], v[50:51], v[16:17] op_sel_hi:[1,1,0]
	v_pk_add_f32 v[30:31], v[30:31], v[30:31] op_sel_hi:[0,1]
	v_pk_add_f32 v[28:29], v[28:29], v[28:29] op_sel_hi:[0,1]
	v_fmamk_f32 v25, v66, 0xba800000, v25
	v_fmamk_f32 v23, v66, 0xba800000, v23
	v_mul_f32_e32 v34, v10, v10
	v_mul_f32_e32 v64, v11, v11
	v_mul_f32_e32 v30, v12, v12
	v_mul_f32_e32 v28, v13, v13
	v_fmamk_f32 v24, v66, 0xba800000, v24
	v_fmac_f32_e32 v22, 0xba800000, v66
	v_mul_f32_e32 v0, v23, v23
	v_mul_f32_e32 v16, v25, v25
	v_pk_add_f32 v[34:35], v[34:35], v[64:65]
	v_pk_add_f32 v[28:29], v[30:31], v[28:29]
	v_fmac_f32_e32 v0, v22, v22
	v_fmac_f32_e32 v16, v24, v24
	v_pk_add_f32 v[28:29], v[34:35], v[28:29]
	v_fmamk_f32 v19, v66, 0xba800000, v19
	v_add_f32_e32 v0, v0, v16
	v_add_f32_e32 v21, v28, v29
	v_fmamk_f32 v16, v66, 0xba800000, v20
	v_fmac_f32_e32 v18, 0xba800000, v66
	v_mul_f32_e32 v20, v19, v19
	v_mul_f32_e32 v28, v17, v17
	v_fmac_f32_e32 v20, v18, v18
	v_fmac_f32_e32 v28, v16, v16
	v_add_f32_e32 v20, v20, v28
	v_fmamk_f32 v9, v66, 0xba800000, v9
	v_fmamk_f32 v7, v66, 0xba800000, v7
	v_add_f32_e32 v0, v0, v20
	v_fmamk_f32 v8, v66, 0xba800000, v8
	v_fmac_f32_e32 v6, 0xba800000, v66
	v_mul_f32_e32 v20, v7, v7
	v_mul_f32_e32 v28, v9, v9
	v_fmac_f32_e32 v20, v6, v6
	v_fmac_f32_e32 v28, v8, v8
	v_add_f32_e32 v20, v20, v28
	ds_bpermute_b32 v28, v58, v21
	v_fmamk_f32 v5, v66, 0xba800000, v5
	v_fmamk_f32 v3, v66, 0xba800000, v3
	v_add_f32_e32 v0, v20, v0
	v_fmamk_f32 v4, v66, 0xba800000, v4
	s_waitcnt lgkmcnt(0)
	v_add_f32_e32 v21, v21, v28
	ds_bpermute_b32 v28, v59, v21
	v_fmac_f32_e32 v2, 0xba800000, v66
	v_mul_f32_e32 v20, v3, v3
	v_mul_f32_e32 v29, v5, v5
	v_fmac_f32_e32 v20, v2, v2
	s_waitcnt lgkmcnt(0)
	v_add_f32_e32 v21, v21, v28
	ds_bpermute_b32 v28, v60, v21
	v_fmac_f32_e32 v29, v4, v4
	v_add_f32_e32 v20, v20, v29
	v_add_f32_e32 v0, v20, v0
	ds_bpermute_b32 v20, v58, v0
	s_waitcnt lgkmcnt(1)
	v_add_f32_e32 v21, v21, v28
	ds_bpermute_b32 v28, v61, v21
	s_waitcnt lgkmcnt(1)
	v_add_f32_e32 v0, v0, v20
	ds_bpermute_b32 v20, v59, v0
	s_waitcnt lgkmcnt(1)
	v_add_f32_e32 v21, v21, v28
	s_nop 1
	v_mov_b32_e32 v28, v108
	v_mov_b32_e32 v29, v109
	v_mov_b32_e32 v30, v110
	v_mov_b32_e32 v31, v111
	s_nop 1
	v_mov_b32_e32 v34, v112
	v_mov_b32_e32 v35, v113
	v_mov_b32_e32 v36, v114
	v_mov_b32_e32 v37, v115
	ds_bpermute_b32 v56, v62, v21
	s_waitcnt lgkmcnt(1)
	v_add_f32_e32 v0, v0, v20
	ds_bpermute_b32 v20, v60, v0
	s_waitcnt lgkmcnt(1)
	v_add_f32_e32 v21, v21, v56
	ds_bpermute_b32 v56, v63, v21
	s_waitcnt lgkmcnt(1)
	v_add_f32_e32 v0, v0, v20
	ds_bpermute_b32 v20, v61, v0
	s_waitcnt lgkmcnt(1)
	v_add_f32_e32 v21, v21, v56
	v_fmamk_f32 v21, v21, 0x3a800000, v202
	v_mul_f32_e32 v56, 0x4f800000, v21
	v_cmp_gt_f32_e32 vcc, s3, v21
	s_waitcnt lgkmcnt(0)
	v_add_f32_e32 v0, v0, v20
	ds_bpermute_b32 v20, v62, v0
	v_cndmask_b32_e32 v21, v21, v56, vcc
	v_sqrt_f32_e32 v56, v21
	s_waitcnt lgkmcnt(0)
	v_add_f32_e32 v0, v0, v20
	v_add_u32_e32 v57, -1, v56
	v_fma_f32 v64, -v57, v56, v21
	v_cmp_ge_f32_e64 s[18:19], 0, v64
	v_add_u32_e32 v64, 1, v56
	ds_bpermute_b32 v20, v63, v0
	v_cndmask_b32_e64 v57, v56, v57, s[18:19]
	v_fma_f32 v56, -v64, v56, v21
	v_cmp_lt_f32_e64 s[18:19], 0, v56
	s_waitcnt lgkmcnt(0)
	v_add_f32_e32 v0, v0, v20
	v_cndmask_b32_e64 v56, v57, v64, s[18:19]
	v_mul_f32_e32 v57, 0x37800000, v56
	v_cndmask_b32_e32 v56, v56, v57, vcc
	v_cmp_class_f32_e32 vcc, v21, v205
	v_fmamk_f32 v0, v0, 0x3a800000, v202
	v_mul_f32_e32 v65, 0x4f800000, v0
	v_cndmask_b32_e32 v21, v56, v21, vcc
	v_div_scale_f32 v56, s[14:15], v21, v21, 1.0
	v_rcp_f32_e32 v57, v56
	v_cmp_gt_f32_e64 s[18:19], s3, v0
	v_fma_f32 v20, -v56, v57, 1.0
	s_nop 0
	v_cndmask_b32_e64 v0, v0, v65, s[18:19]
	v_fmac_f32_e32 v57, v20, v57
	v_div_scale_f32 v20, vcc, 1.0, v21, 1.0
	v_sqrt_f32_e32 v65, v0
	v_mul_f32_e32 v64, v20, v57
	v_fma_f32 v66, -v56, v64, v20
	v_fmac_f32_e32 v64, v66, v57
	v_fma_f32 v20, -v56, v64, v20
	v_add_u32_e32 v56, -1, v65
	v_fma_f32 v66, -v56, v65, v0
	v_cmp_ge_f32_e64 s[20:21], 0, v66
	v_add_u32_e32 v66, 1, v65
	v_div_fmas_f32 v20, v20, v57, v64
	v_cndmask_b32_e64 v56, v65, v56, s[20:21]
	v_fma_f32 v65, -v66, v65, v0
	v_cmp_lt_f32_e64 s[20:21], 0, v65
	s_nop 1
	v_cndmask_b32_e64 v56, v56, v66, s[20:21]
	v_mul_f32_e32 v65, 0x37800000, v56
	v_cndmask_b32_e64 v56, v56, v65, s[18:19]
	v_cmp_class_f32_e64 s[18:19], v0, v205
	s_nop 1
	v_cndmask_b32_e64 v0, v56, v0, s[18:19]
	v_div_scale_f32 v65, s[2:3], v0, v0, 1.0
	v_rcp_f32_e32 v66, v65
	v_div_fixup_f32 v56, v20, v21, 1.0
	s_mov_b64 s[2:3], -1
	v_fma_f32 v20, -v65, v66, 1.0
	v_fmac_f32_e32 v66, v20, v66
	v_div_scale_f32 v20, vcc, 1.0, v0, 1.0
	v_mul_f32_e32 v21, v20, v66
	v_fma_f32 v57, -v65, v21, v20
	v_fmac_f32_e32 v21, v57, v66
	v_fma_f32 v20, -v65, v21, v20
	v_div_fmas_f32 v20, v20, v66, v21
	v_mov_b32_e32 v57, v56
	v_div_fixup_f32 v0, v20, v0, 1.0
	v_pk_mul_f32 v[20:21], v[54:55], v[56:57] op_sel_hi:[1,0]
	v_pk_mul_f32 v[32:33], v[32:33], v[56:57] op_sel_hi:[1,0]
	s_nop 0
	v_pk_fma_f32 v[64:65], v[28:29], v[20:21], v[34:35]
	v_pk_fma_f32 v[66:67], v[30:31], v[32:33], v[36:37]
	v_pk_mul_f32 v[20:21], v[26:27], v[56:57]
	global_store_dwordx4 v[46:47], v[64:67], off
	s_cbranch_scc1 .LBB0_2106
; DI void ln_rows2_f32(float* xa, float* xb, const float* g, const float* b, int lane, bool two) {
;     ...
;     for (int j = 0; j < 4; ++j) { const f32x4 gg = ((const f32x4*)g)[lane + 64 * j], bb = ((const f32x4*)b)[lane + 64 * j];
; #pragma unroll
;         for (int r = 0; r < 2; ++r) if (r == 0 || two) xr[r][lane + 64 * j] = v[r][j] * rstd[r] * gg + bb; }
	v_pk_mul_f32 v[24:25], v[24:25], v[0:1] op_sel_hi:[1,0]
	v_pk_mul_f32 v[22:23], v[22:23], v[0:1] op_sel_hi:[1,0]
	v_pk_fma_f32 v[24:25], v[30:31], v[24:25], v[36:37]
	v_pk_fma_f32 v[22:23], v[28:29], v[22:23], v[34:35]
	global_store_dwordx4 v[48:49], v[22:25], off
	s_nop 1
	v_mov_b32_e32 v22, v116
	v_mov_b32_e32 v23, v117
	v_mov_b32_e32 v24, v118
	v_mov_b32_e32 v25, v119
	s_nop 0
	s_nop 1
	v_mov_b32_e32 v26, v120
	v_mov_b32_e32 v27, v121
	v_mov_b32_e32 v28, v122
	v_mov_b32_e32 v29, v123
	v_mov_b32_e32 v30, v56
	v_mov_b32_e32 v31, v56
	v_pk_mul_f32 v[32:33], v[16:17], v[0:1] op_sel_hi:[1,0]
	v_pk_mul_f32 v[16:17], v[52:53], v[30:31]
	v_pk_mul_f32 v[34:35], v[18:19], v[0:1] op_sel_hi:[1,0]
	s_mov_b64 s[2:3], 0
	s_nop 0
	v_pk_fma_f32 v[18:19], v[16:17], v[24:25], v[28:29]
	v_pk_fma_f32 v[16:17], v[20:21], v[22:23], v[26:27]
	v_pk_fma_f32 v[24:25], v[32:33], v[24:25], v[28:29]
	v_pk_fma_f32 v[22:23], v[34:35], v[22:23], v[26:27]
	global_store_dwordx4 v[46:47], v[16:19], off offset:1024
	global_store_dwordx4 v[48:49], v[22:25], off offset:1024

; DI float bperm(float v, int srclane) { return __int_as_float(__builtin_amdgcn_ds_bpermute(srclane << 2, __float_as_int(v))); }
; DI void ln_rows2_bf16(bf16_t* xa, bf16_t* xb, const float* g, const float* b, int lane, bool two) {
;     u32x4* xr[2] = {(u32x4*)xa, (u32x4*)xb}; float v[2][2][8]; float s[2] = {0.f, 0.f}, s2[2] = {0.f, 0.f}, mean[2], rstd[2];
;     u32x4 raw[2][2];
; #pragma unroll
;     for (int r = 0; r < 2; ++r)
; #pragma unroll
;         for (int j = 0; j < 2; ++j) raw[r][j] = xr[r][lane + 64 * j];
; #pragma unroll
;     for (int r = 0; r < 2; ++r)
; #pragma unroll
;         for (int j = 0; j < 2; ++j) { unpack8(raw[r][j], v[r][j]);
; #pragma unroll
;             for (int k = 0; k < 8; ++k) s[r] += v[r][j][k]; }
; #pragma unroll
;     for (int o = 1; o < 64; o <<= 1) { s[0] += bperm(s[0], lane ^ o); s[1] += bperm(s[1], lane ^ o); }
; __global__ void __launch_bounds__(512, 2) hybrid_fwd(Args unused_args) {
;     ...
;           if (l == 0) { for (int m = gw; m < T; m += 2 * NGW) { const int m2 = m + NGW < T ? m + NGW : m; ln_rows2_bf16(XB + (size_t)m * DMODEL, XB + (size_t)m2 * DMODEL, P.ln2g, P.ln2b, lane, m2 != m); }
.LBB0_2117:
	s_add_i32 s13, s24, s7
	s_cmp_lt_i32 s13, 0x8000
	s_cselect_b32 s2, s13, s24
	s_ashr_i32 s25, s24, 31
	s_lshl_b64 s[14:15], s[24:25], 11
	s_ashr_i32 s3, s2, 31
	v_lshl_add_u64 v[30:31], v[26:27], 0, s[14:15]
	s_lshl_b64 s[14:15], s[2:3], 11
	v_lshl_add_u64 v[28:29], v[26:27], 0, s[14:15]
	global_load_dwordx4 v[6:9], v[30:31], off offset:1024
	global_load_dwordx4 v[10:13], v[30:31], off
	global_load_dwordx4 v[14:17], v[28:29], off offset:1024
	global_load_dwordx4 v[32:35], v[28:29], off
	s_mov_b32 s3, 0xf800000
	s_cmp_lg_u32 s24, s2
	s_cselect_b64 s[20:21], -1, 0
	s_cmp_eq_u32 s24, s2
	s_waitcnt vmcnt(3)
	v_lshlrev_b32_e32 v2, 16, v9
	s_waitcnt vmcnt(2)
	v_lshlrev_b32_e32 v42, 16, v10
	s_waitcnt vmcnt(0)
	v_mov_b32_e32 v120, s13
	v_add_u32_e32 v120, s7, v120
	v_mov_b32_e32 v122, 0x8000
	v_cmp_lt_i32_e64 s[14:15], v120, v122
	v_add_u32_e32 v122, s7, v120
	v_lshlrev_b32_e32 v120, 11, v120
	v_lshlrev_b32_e32 v122, 11, v122
	v_mov_b32_e32 v121, 0
	v_mov_b32_e32 v123, 0
	v_lshl_add_u64 v[120:121], v[26:27], 0, v[120:121]
	v_lshl_add_u64 v[122:123], v[26:27], 0, v[122:123]
	s_mov_b64 exec, s[14:15]
	global_load_dwordx4 v[124:127], v[120:121], off
	global_load_dwordx4 v[124:127], v[120:121], off offset:1024
	global_load_dwordx4 v[124:127], v[122:123], off
	global_load_dwordx4 v[124:127], v[122:123], off offset:1024
	s_mov_b64 exec, -1
	v_lshlrev_b32_e32 v52, 16, v32
	v_and_b32_e32 v43, 0xffff0000, v10
	v_and_b32_e32 v53, 0xffff0000, v32
	v_add_f32_e32 v0, 0, v42
	v_add_f32_e32 v32, 0, v52
	v_lshlrev_b32_e32 v40, 16, v12
	v_and_b32_e32 v41, 0xffff0000, v12
	v_lshlrev_b32_e32 v12, 16, v11
	v_lshlrev_b32_e32 v50, 16, v34
	v_and_b32_e32 v51, 0xffff0000, v34
	v_lshlrev_b32_e32 v34, 16, v33
	v_add_f32_e32 v0, v0, v43
	v_add_f32_e32 v32, v32, v53
	v_and_b32_e32 v3, 0xffff0000, v9
	v_lshlrev_b32_e32 v4, 16, v8
	v_and_b32_e32 v5, 0xffff0000, v8
	v_lshlrev_b32_e32 v8, 16, v7
	v_and_b32_e32 v9, 0xffff0000, v7
	v_lshlrev_b32_e32 v36, 16, v6
	v_and_b32_e32 v37, 0xffff0000, v6
	v_lshlrev_b32_e32 v6, 16, v13
	v_and_b32_e32 v7, 0xffff0000, v13
	v_and_b32_e32 v13, 0xffff0000, v11
	v_lshlrev_b32_e32 v10, 16, v17
	v_and_b32_e32 v11, 0xffff0000, v17
	v_lshlrev_b32_e32 v58, 16, v16
	v_and_b32_e32 v59, 0xffff0000, v16
	v_lshlrev_b32_e32 v16, 16, v15
	v_and_b32_e32 v17, 0xffff0000, v15
	v_lshlrev_b32_e32 v66, 16, v14
	v_and_b32_e32 v67, 0xffff0000, v14
	v_lshlrev_b32_e32 v14, 16, v35
	v_and_b32_e32 v15, 0xffff0000, v35
	v_and_b32_e32 v35, 0xffff0000, v33
	v_add_f32_e32 v0, v0, v12
	v_add_f32_e32 v32, v32, v34
	v_add_f32_e32 v0, v0, v13
	v_add_f32_e32 v32, v32, v35
	v_add_f32_e32 v0, v0, v40
	v_add_f32_e32 v32, v32, v50
	v_add_f32_e32 v0, v0, v41
	v_add_f32_e32 v32, v32, v51
	v_add_f32_e32 v0, v0, v6
	v_add_f32_e32 v32, v32, v14
	v_add_f32_e32 v0, v0, v7
	v_add_f32_e32 v32, v32, v15
	v_add_f32_e32 v0, v0, v36
	v_add_f32_e32 v32, v32, v66
	v_add_f32_e32 v0, v0, v37
	v_add_f32_e32 v32, v32, v67
	v_add_f32_e32 v0, v0, v8
	v_add_f32_e32 v32, v32, v16
	v_add_f32_e32 v0, v0, v9
	v_add_f32_e32 v32, v32, v17
	v_add_f32_e32 v0, v0, v4
	v_add_f32_e32 v32, v32, v58
	v_add_f32_e32 v0, v0, v5
	v_add_f32_e32 v32, v32, v59
	v_add_f32_e32 v0, v0, v2
	v_add_f32_e32 v32, v32, v10
	v_add_f32_e32 v0, v0, v3
	v_add_f32_e32 v32, v32, v11
	ds_bpermute_b32 v33, v61, v0
	ds_bpermute_b32 v44, v61, v32
	s_waitcnt lgkmcnt(1)
	v_add_f32_e32 v0, v0, v33
	s_waitcnt lgkmcnt(0)
	v_add_f32_e32 v32, v32, v44
	ds_bpermute_b32 v33, v62, v0
	ds_bpermute_b32 v44, v62, v32
	s_waitcnt lgkmcnt(1)
	v_add_f32_e32 v0, v0, v33
	s_waitcnt lgkmcnt(0)
	v_add_f32_e32 v32, v32, v44
	ds_bpermute_b32 v33, v63, v0
	ds_bpermute_b32 v44, v63, v32
	s_waitcnt lgkmcnt(1)
	v_add_f32_e32 v0, v0, v33
	s_waitcnt lgkmcnt(0)
	v_add_f32_e32 v32, v32, v44
	ds_bpermute_b32 v33, v64, v0
	ds_bpermute_b32 v44, v64, v32
	s_waitcnt lgkmcnt(1)
	v_add_f32_e32 v0, v0, v33
	s_waitcnt lgkmcnt(0)
	v_add_f32_e32 v32, v32, v44
	ds_bpermute_b32 v33, v65, v0
	ds_bpermute_b32 v44, v65, v32
	s_waitcnt lgkmcnt(1)
	v_add_f32_e32 v0, v0, v33
	s_waitcnt lgkmcnt(0)
	v_add_f32_e32 v32, v32, v44
	ds_bpermute_b32 v33, v60, v0
	ds_bpermute_b32 v44, v60, v32
	s_waitcnt lgkmcnt(1)
	v_add_f32_e32 v0, v0, v33
	s_waitcnt lgkmcnt(0)
	v_add_f32_e32 v32, v32, v44
	v_mul_f32_e32 v0, 0x3a800000, v0
	v_mul_f32_e32 v32, 0x3a800000, v32
	v_pk_add_f32 v[68:69], v[42:43], v[0:1] op_sel_hi:[1,0] neg_lo:[0,1] neg_hi:[0,1]
	v_pk_add_f32 v[56:57], v[52:53], v[32:33] op_sel_hi:[1,0] neg_lo:[0,1] neg_hi:[0,1]
	v_pk_add_f32 v[48:49], v[2:3], v[0:1] op_sel_hi:[1,0] neg_lo:[0,1] neg_hi:[0,1]
	v_pk_add_f32 v[54:55], v[34:35], v[32:33] op_sel_hi:[1,0] neg_lo:[0,1] neg_hi:[0,1]
	v_pk_add_f32 v[34:35], v[58:59], v[32:33] op_sel_hi:[1,0] neg_lo:[0,1] neg_hi:[0,1]
	v_pk_mul_f32 v[2:3], v[68:69], v[68:69]
	v_pk_mul_f32 v[58:59], v[56:57], v[56:57]
	v_pk_add_f32 v[70:71], v[12:13], v[0:1] op_sel_hi:[1,0] neg_lo:[0,1] neg_hi:[0,1]
	v_pk_add_f32 v[72:73], v[40:41], v[0:1] op_sel_hi:[1,0] neg_lo:[0,1] neg_hi:[0,1]
	v_pk_add_f32 v[74:75], v[6:7], v[0:1] op_sel_hi:[1,0] neg_lo:[0,1] neg_hi:[0,1]
	v_pk_add_f32 v[42:43], v[36:37], v[0:1] op_sel_hi:[1,0] neg_lo:[0,1] neg_hi:[0,1]
	v_pk_add_f32 v[44:45], v[8:9], v[0:1] op_sel_hi:[1,0] neg_lo:[0,1] neg_hi:[0,1]
	v_pk_add_f32 v[46:47], v[4:5], v[0:1] op_sel_hi:[1,0] neg_lo:[0,1] neg_hi:[0,1]
	v_pk_add_f32 v[40:41], v[66:67], v[32:33] op_sel_hi:[1,0] neg_lo:[0,1] neg_hi:[0,1]
	v_pk_mul_f32 v[66:67], v[54:55], v[54:55]
	v_add_f32_e32 v0, v2, v3
	v_add_f32_e32 v2, v58, v59
	v_pk_add_f32 v[52:53], v[50:51], v[32:33] op_sel_hi:[1,0] neg_lo:[0,1] neg_hi:[0,1]
	v_add_f32_e32 v2, v66, v2
	v_pk_mul_f32 v[76:77], v[52:53], v[52:53]
	v_add_f32_e32 v2, v67, v2
	v_pk_add_f32 v[50:51], v[14:15], v[32:33] op_sel_hi:[1,0] neg_lo:[0,1] neg_hi:[0,1]
	v_add_f32_e32 v2, v76, v2
	v_pk_mul_f32 v[78:79], v[50:51], v[50:51]
	v_add_f32_e32 v2, v77, v2
	v_add_f32_e32 v2, v78, v2
	v_pk_mul_f32 v[80:81], v[40:41], v[40:41]
	v_add_f32_e32 v2, v79, v2
	v_pk_add_f32 v[36:37], v[16:17], v[32:33] op_sel_hi:[1,0] neg_lo:[0,1] neg_hi:[0,1]
	v_add_f32_e32 v2, v80, v2
	v_pk_mul_f32 v[82:83], v[36:37], v[36:37]
	v_add_f32_e32 v2, v81, v2
	v_add_f32_e32 v2, v82, v2
	v_pk_mul_f32 v[84:85], v[34:35], v[34:35]
	v_add_f32_e32 v2, v83, v2
	v_pk_add_f32 v[32:33], v[10:11], v[32:33] op_sel_hi:[1,0] neg_lo:[0,1] neg_hi:[0,1]
	v_add_f32_e32 v2, v84, v2
	v_pk_mul_f32 v[86:87], v[32:33], v[32:33]
	v_add_f32_e32 v2, v85, v2
	v_add_f32_e32 v2, v86, v2
	v_add_f32_e32 v2, v87, v2
	ds_bpermute_b32 v3, v61, v2
	v_pk_mul_f32 v[4:5], v[70:71], v[70:71]
	v_pk_mul_f32 v[6:7], v[72:73], v[72:73]
	v_add_f32_e32 v0, v4, v0
	v_add_f32_e32 v0, v5, v0
	s_waitcnt lgkmcnt(0)
; DI float bperm(float v, int srclane) { return __int_as_float(__builtin_amdgcn_ds_bpermute(srclane << 2, __float_as_int(v))); }
; DI u32x4 pack8(const float (&v)[8]) { u32x4 w; w.x = pk2(v[0], v[1]); w.y = pk2(v[2], v[3]); w.z = pk2(v[4], v[5]); w.w = pk2(v[6], v[7]); return w; }
; DI void ln_rows2_bf16(bf16_t* xa, bf16_t* xb, const float* g, const float* b, int lane, bool two) {
;     ...
;     for (int r = 0; r < 2; ++r) { mean[r] = s[r] * (1.f / 1024.f);
; #pragma unroll
;         for (int j = 0; j < 2; ++j)
; #pragma unroll
;             for (int k = 0; k < 8; ++k) { v[r][j][k] -= mean[r]; s2[r] += v[r][j][k] * v[r][j][k]; } }
; #pragma unroll
;     for (int o = 1; o < 64; o <<= 1) { s2[0] += bperm(s2[0], lane ^ o); s2[1] += bperm(s2[1], lane ^ o); }
; #pragma unroll
;     for (int r = 0; r < 2; ++r) rstd[r] = 1.f / sqrtf(s2[r] * (1.f / 1024.f) + EPS);
; #pragma unroll
;     for (int j = 0; j < 2; ++j) { const int c0 = (lane + 64 * j) * 8; const f32x4 g0 = *(const f32x4*)(g + c0), g1 = *(const f32x4*)(g + c0 + 4), b0 = *(const f32x4*)(b + c0), b1 = *(const f32x4*)(b + c0 + 4);
; #pragma unroll
;         for (int r = 0; r < 2; ++r) { float o[8];
; #pragma unroll
;             for (int k = 0; k < 4; ++k) { o[k] = v[r][j][k] * rstd[r] * g0[k] + b0[k]; o[4 + k] = v[r][j][4 + k] * rstd[r] * g1[k] + b1[k]; }
;             if (r == 0 || two) xr[r][lane + 64 * j] = pack8(o); } }
	v_add_f32_e32 v2, v2, v3
	v_add_f32_e32 v0, v6, v0
	ds_bpermute_b32 v3, v62, v2
	v_pk_mul_f32 v[8:9], v[74:75], v[74:75]
	v_add_f32_e32 v0, v7, v0
	v_add_f32_e32 v0, v8, v0
	v_pk_mul_f32 v[10:11], v[42:43], v[42:43]
	v_add_f32_e32 v0, v9, v0
	v_add_f32_e32 v0, v10, v0
	v_pk_mul_f32 v[12:13], v[44:45], v[44:45]
	v_add_f32_e32 v0, v11, v0
	s_waitcnt lgkmcnt(0)
	v_add_f32_e32 v2, v2, v3
	v_add_f32_e32 v0, v12, v0
	ds_bpermute_b32 v3, v63, v2
	v_pk_mul_f32 v[14:15], v[46:47], v[46:47]
	v_add_f32_e32 v0, v13, v0
	v_add_f32_e32 v0, v14, v0
	v_pk_mul_f32 v[16:17], v[48:49], v[48:49]
	v_add_f32_e32 v0, v15, v0
	v_add_f32_e32 v0, v16, v0
	v_add_f32_e32 v0, v17, v0
	s_waitcnt lgkmcnt(0)
	v_add_f32_e32 v2, v2, v3
	ds_bpermute_b32 v4, v61, v0
	ds_bpermute_b32 v3, v64, v2
	s_waitcnt lgkmcnt(1)
	v_add_f32_e32 v0, v0, v4
	s_waitcnt lgkmcnt(0)
	v_add_f32_e32 v11, v2, v3
	ds_bpermute_b32 v10, v62, v0
	ds_bpermute_b32 v12, v65, v11
	s_nop 1
	v_mov_b32_e32 v2, v140
	v_mov_b32_e32 v3, v141
	v_mov_b32_e32 v4, v142
	v_mov_b32_e32 v5, v143
	s_nop 1
	v_mov_b32_e32 v6, v144
	v_mov_b32_e32 v7, v145
	v_mov_b32_e32 v8, v146
	v_mov_b32_e32 v9, v147
	s_waitcnt lgkmcnt(1)
	v_add_f32_e32 v0, v0, v10
	s_waitcnt lgkmcnt(0)
	v_add_f32_e32 v59, v11, v12
	s_nop 1
	v_mov_b32_e32 v10, v148
	v_mov_b32_e32 v11, v149
	v_mov_b32_e32 v12, v150
	v_mov_b32_e32 v13, v151
	s_nop 1
	v_mov_b32_e32 v14, v152
	v_mov_b32_e32 v15, v153
	v_mov_b32_e32 v16, v154
	v_mov_b32_e32 v17, v155
	ds_bpermute_b32 v66, v60, v59
	ds_bpermute_b32 v58, v63, v0
	s_waitcnt lgkmcnt(1)
	v_add_f32_e32 v59, v59, v66
	v_fmamk_f32 v59, v59, 0x3a800000, v202
	s_waitcnt lgkmcnt(0)
	v_add_f32_e32 v0, v0, v58
	v_mul_f32_e32 v66, 0x4f800000, v59
	v_cmp_gt_f32_e32 vcc, s3, v59
	ds_bpermute_b32 v58, v64, v0
	s_waitcnt lgkmcnt(0)
	v_add_f32_e32 v0, v0, v58
	v_cndmask_b32_e32 v59, v59, v66, vcc
	v_sqrt_f32_e32 v66, v59
	s_nop 0
	v_add_u32_e32 v58, -1, v66
	v_add_u32_e32 v67, 1, v66
	v_fma_f32 v76, -v58, v66, v59
	v_fma_f32 v77, -v67, v66, v59
	v_cmp_ge_f32_e64 s[16:17], 0, v76
	s_nop 1
	v_cndmask_b32_e64 v58, v66, v58, s[16:17]
	v_cmp_lt_f32_e64 s[16:17], 0, v77
	s_nop 1
	v_cndmask_b32_e64 v58, v58, v67, s[16:17]
	ds_bpermute_b32 v67, v65, v0
	v_mul_f32_e32 v66, 0x37800000, v58
	v_cndmask_b32_e32 v58, v58, v66, vcc
	v_cmp_class_f32_e32 vcc, v59, v205
	s_waitcnt lgkmcnt(0)
	v_add_f32_e32 v0, v0, v67
	ds_bpermute_b32 v67, v60, v0
	v_cndmask_b32_e32 v58, v58, v59, vcc
	v_div_scale_f32 v59, s[14:15], v58, v58, 1.0
	v_rcp_f32_e32 v66, v59
	s_waitcnt lgkmcnt(0)
	v_add_f32_e32 v0, v0, v67
	v_fmamk_f32 v0, v0, 0x3a800000, v202
	v_mul_f32_e32 v67, 0x4f800000, v0
	v_cmp_gt_f32_e64 s[16:17], s3, v0
	v_fma_f32 v76, -v59, v66, 1.0
	v_fmac_f32_e32 v66, v76, v66
	v_cndmask_b32_e64 v0, v0, v67, s[16:17]
	v_div_scale_f32 v76, vcc, 1.0, v58, 1.0
	v_sqrt_f32_e32 v67, v0
	v_mul_f32_e32 v77, v76, v66
	v_fma_f32 v78, -v59, v77, v76
	v_fmac_f32_e32 v77, v78, v66
	v_fma_f32 v59, -v59, v77, v76
	v_add_u32_e32 v76, -1, v67
	v_fma_f32 v78, -v76, v67, v0
	v_cmp_ge_f32_e64 s[18:19], 0, v78
	v_add_u32_e32 v78, 1, v67
	s_nop 0
	v_cndmask_b32_e64 v76, v67, v76, s[18:19]
	v_fma_f32 v67, -v78, v67, v0
	v_cmp_lt_f32_e64 s[18:19], 0, v67
	s_nop 1
	v_cndmask_b32_e64 v67, v76, v78, s[18:19]
	v_mul_f32_e32 v76, 0x37800000, v67
	v_cndmask_b32_e64 v67, v67, v76, s[16:17]
	v_cmp_class_f32_e64 s[16:17], v0, v205
	s_nop 1
	v_cndmask_b32_e64 v67, v67, v0, s[16:17]
	v_div_scale_f32 v76, s[2:3], v67, v67, 1.0
	v_rcp_f32_e32 v78, v76
	v_div_fmas_f32 v0, v59, v66, v77
	v_div_fixup_f32 v0, v0, v58, 1.0
	v_fma_f32 v58, -v76, v78, 1.0
	v_fmac_f32_e32 v78, v58, v78
	v_div_scale_f32 v58, vcc, 1.0, v67, 1.0
	v_mul_f32_e32 v59, v58, v78
	v_fma_f32 v66, -v76, v59, v58
	v_fmac_f32_e32 v59, v66, v78
	v_fma_f32 v58, -v76, v59, v58
	v_div_fmas_f32 v58, v58, v78, v59
	v_div_fixup_f32 v58, v58, v67, 1.0
	v_pk_mul_f32 v[66:67], v[68:69], v[58:59] op_sel_hi:[1,0]
	v_pk_mul_f32 v[68:69], v[70:71], v[58:59] op_sel_hi:[1,0]
	v_pk_mul_f32 v[70:71], v[72:73], v[58:59] op_sel_hi:[1,0]
	v_pk_mul_f32 v[72:73], v[74:75], v[58:59] op_sel_hi:[1,0]
	s_nop 0
	v_pk_fma_f32 v[66:67], v[2:3], v[66:67], v[6:7]
	v_pk_fma_f32 v[68:69], v[4:5], v[68:69], v[8:9]
	s_nop 0
	v_pk_fma_f32 v[70:71], v[10:11], v[70:71], v[14:15]
	v_pk_fma_f32 v[72:73], v[12:13], v[72:73], v[16:17]
	v_cvt_pk_bf16_f32 v66, v66, v67
	v_cvt_pk_bf16_f32 v67, v68, v69
	v_cvt_pk_bf16_f32 v68, v70, v71
	v_cvt_pk_bf16_f32 v69, v72, v73
	global_store_dwordx4 v[30:31], v[66:69], off
	s_cbranch_scc1 .LBB0_2119
	v_pk_mul_f32 v[56:57], v[56:57], v[0:1] op_sel_hi:[1,0]
	s_nop 0
	v_pk_fma_f32 v[2:3], v[2:3], v[56:57], v[6:7]
	v_pk_mul_f32 v[6:7], v[54:55], v[0:1] op_sel_hi:[1,0]
	v_cvt_pk_bf16_f32 v2, v2, v3
	v_pk_fma_f32 v[4:5], v[4:5], v[6:7], v[8:9]
	v_pk_mul_f32 v[6:7], v[52:53], v[0:1] op_sel_hi:[1,0]
	v_pk_mul_f32 v[8:9], v[50:51], v[0:1] op_sel_hi:[1,0]
	v_pk_fma_f32 v[6:7], v[10:11], v[6:7], v[14:15]
	v_pk_fma_f32 v[8:9], v[12:13], v[8:9], v[16:17]
	v_cvt_pk_bf16_f32 v3, v4, v5
	v_cvt_pk_bf16_f32 v4, v6, v7
	v_cvt_pk_bf16_f32 v5, v8, v9
	global_store_dwordx4 v[28:29], v[2:5], off
